# prologue tr_matrix: 32 serialized kscale loads hoisted and issued up front (counted vmcnt), on top of v39
# speedup vs baseline: 1.0085x; 1.0085x over previous
; #define LDS_WAIT() asm volatile("s_waitcnt lgkmcnt(0)" ::: "memory")
; __device__ __forceinline__ void tr_matrix(const float* W, int ldw, int K, int N, bf16* WT, int mode, const float* kscale, float* scr, int gw, int NGW, int lane) {
;     ...
;     for (int it = gw; it < nitems; it += NGW) {
;         const int kb = it / nblk, nb = it % nblk, k0 = 64 * kb, n0 = 32 * nb;
; #pragma unroll
;         for (int i = 0; i < 32; ++i) { const int kk = 2 * i + (lane >> 5); scr[kk * 33 + (lane & 31)] = kscale ? nx[i] * kscale[k0 + kk] : nx[i]; }
;         if (it + NGW < nitems) { const int kb2 = (it + NGW) / nblk, nb2 = (it + NGW) % nblk;
; #pragma unroll
;             for (int i = 0; i < 32; ++i) { const int kk = 2 * i + (lane >> 5); nx[i] = W[(size_t)(64 * kb2 + kk) * ldw + 32 * nb2 + (lane & 31)]; } }
;         LDS_WAIT();
.LBB0_36:
	v_sub_u32_e32 v51, 0, v86
	v_max_i32_e32 v51, v86, v51
	v_mul_hi_u32 v87, v51, v3
	v_mul_lo_u32 v88, v87, s6
	v_sub_u32_e32 v51, v51, v88
	v_add_u32_e32 v88, 1, v87
	v_cmp_le_u32_e32 vcc, s6, v51
	v_ashrrev_i32_e32 v50, 31, v86
	s_nop 0
	v_cndmask_b32_e32 v87, v87, v88, vcc
	v_subrev_u32_e32 v88, s6, v51
	v_cndmask_b32_e32 v51, v51, v88, vcc
	v_add_u32_e32 v88, 1, v87
	v_cmp_le_u32_e32 vcc, s6, v51
	s_nop 1
	v_cndmask_b32_e32 v51, v87, v88, vcc
	v_xor_b32_e32 v51, v51, v50
	v_sub_u32_e32 v87, v51, v50
	v_cndmask_b32_e64 v51, 0, 1, s[22:23]
	v_lshlrev_b32_e32 v50, 6, v87
	v_cmp_ne_u32_e64 s[4:5], 1, v51
	s_andn2_b64 vcc, exec, s[22:23]
	s_cbranch_vccnz .Lks_none
	v_or_b32_e32 v88, v50, v36
	v_ashrrev_i32_e32 v89, 31, v88
	v_lshl_add_u64 v[88:89], v[88:89], 2, s[12:13]
	v_ashrrev_i32_e32 v51, 31, v50
	s_waitcnt vmcnt(31)
	global_load_dword v113, v[88:89], off
	global_load_dword v114, v[88:89], off offset:8
	global_load_dword v115, v[88:89], off offset:16
	global_load_dword v116, v[88:89], off offset:24
	global_load_dword v117, v[88:89], off offset:32
	global_load_dword v118, v[88:89], off offset:40
	global_load_dword v119, v[88:89], off offset:48
	global_load_dword v120, v[88:89], off offset:56
	global_load_dword v121, v[88:89], off offset:64
	global_load_dword v122, v[88:89], off offset:72
	global_load_dword v123, v[88:89], off offset:80
	global_load_dword v124, v[88:89], off offset:88
	global_load_dword v125, v[88:89], off offset:96
	global_load_dword v126, v[88:89], off offset:104
	global_load_dword v127, v[88:89], off offset:112
	global_load_dword v128, v[88:89], off offset:120
	global_load_dword v129, v[88:89], off offset:128
	global_load_dword v130, v[88:89], off offset:136
	global_load_dword v131, v[88:89], off offset:144
	global_load_dword v132, v[88:89], off offset:152
	global_load_dword v133, v[88:89], off offset:160
	global_load_dword v134, v[88:89], off offset:168
	global_load_dword v135, v[88:89], off offset:176
	global_load_dword v136, v[88:89], off offset:184
	global_load_dword v137, v[88:89], off offset:192
	global_load_dword v138, v[88:89], off offset:200
	global_load_dword v139, v[88:89], off offset:208
	global_load_dword v140, v[88:89], off offset:216
	global_load_dword v141, v[88:89], off offset:224
	global_load_dword v142, v[88:89], off offset:232
	global_load_dword v143, v[88:89], off offset:240
	global_load_dword v148, v[88:89], off offset:248
	s_waitcnt vmcnt(31)
	v_mul_f32_e32 v89, v4, v113
	ds_write_b32 v52, v89
	s_waitcnt vmcnt(30)
	v_mul_f32_e32 v88, v5, v114
	ds_write_b32 v53, v88
	s_waitcnt vmcnt(29)
	v_mul_f32_e32 v89, v6, v115
	ds_write_b32 v54, v89
	s_waitcnt vmcnt(28)
	v_mul_f32_e32 v88, v7, v116
	ds_write_b32 v55, v88
	s_waitcnt vmcnt(27)
	v_mul_f32_e32 v89, v8, v117
	ds_write_b32 v56, v89
	s_waitcnt vmcnt(26)
	v_mul_f32_e32 v88, v9, v118
	ds_write_b32 v57, v88
	s_waitcnt vmcnt(25)
	v_mul_f32_e32 v89, v10, v119
	ds_write_b32 v58, v89
	s_waitcnt vmcnt(24)
	v_mul_f32_e32 v88, v11, v120
	ds_write_b32 v59, v88
	s_waitcnt vmcnt(23)
	v_mul_f32_e32 v89, v12, v121
	ds_write_b32 v60, v89
	s_waitcnt vmcnt(22)
	v_mul_f32_e32 v88, v13, v122
	ds_write_b32 v61, v88
	s_waitcnt vmcnt(21)
	v_mul_f32_e32 v89, v14, v123
	ds_write_b32 v62, v89
	s_waitcnt vmcnt(20)
	v_mul_f32_e32 v88, v15, v124
	ds_write_b32 v63, v88
	s_waitcnt vmcnt(19)
	v_mul_f32_e32 v89, v16, v125
	ds_write_b32 v64, v89
	s_waitcnt vmcnt(18)
	v_mul_f32_e32 v88, v17, v126
	ds_write_b32 v65, v88
	s_waitcnt vmcnt(17)
	v_mul_f32_e32 v89, v18, v127
	ds_write_b32 v66, v89
	s_waitcnt vmcnt(16)
	v_mul_f32_e32 v88, v19, v128
	ds_write_b32 v67, v88
	s_waitcnt vmcnt(15)
	v_mul_f32_e32 v89, v20, v129
	ds_write_b32 v68, v89
	s_waitcnt vmcnt(14)
	v_mul_f32_e32 v88, v21, v130
	ds_write_b32 v69, v88
	s_waitcnt vmcnt(13)
	v_mul_f32_e32 v89, v22, v131
	ds_write_b32 v70, v89
	s_waitcnt vmcnt(12)
	v_mul_f32_e32 v88, v23, v132
	ds_write_b32 v71, v88
	s_waitcnt vmcnt(11)
	v_mul_f32_e32 v89, v24, v133
	ds_write_b32 v72, v89
	s_waitcnt vmcnt(10)
	v_mul_f32_e32 v88, v25, v134
	ds_write_b32 v73, v88
	s_waitcnt vmcnt(9)
	v_mul_f32_e32 v89, v26, v135
	ds_write_b32 v74, v89
	s_waitcnt vmcnt(8)
	v_mul_f32_e32 v88, v27, v136
	ds_write_b32 v75, v88
	s_waitcnt vmcnt(7)
	v_mul_f32_e32 v89, v28, v137
	ds_write_b32 v76, v89
	s_waitcnt vmcnt(6)
	v_mul_f32_e32 v88, v29, v138
	ds_write_b32 v77, v88
	s_waitcnt vmcnt(5)
	v_mul_f32_e32 v89, v30, v139
	ds_write_b32 v78, v89
	s_waitcnt vmcnt(4)
	v_mul_f32_e32 v88, v31, v140
	ds_write_b32 v79, v88
	s_waitcnt vmcnt(3)
	v_mul_f32_e32 v89, v32, v141
	ds_write_b32 v80, v89
	s_waitcnt vmcnt(2)
	v_mul_f32_e32 v88, v33, v142
	ds_write_b32 v81, v88
	s_waitcnt vmcnt(1)
	v_mul_f32_e32 v89, v34, v143
	ds_write_b32 v82, v89
	s_waitcnt vmcnt(0)
	v_mul_f32_e32 v88, v35, v148
	s_branch .LBB0_100
.Lks_none:
	s_waitcnt vmcnt(31)
	v_mov_b32_e32 v51, v4
	s_cbranch_vccnz .LBB0_38
	v_or_b32_e32 v88, v50, v36
	v_ashrrev_i32_e32 v89, 31, v88
	v_lshl_add_u64 v[88:89], v[88:89], 2, s[12:13]
	global_load_dword v51, v[88:89], off
	s_waitcnt vmcnt(0)
	v_mul_f32_e32 v51, v4, v51
